# carried-buffer copies: the workgroups that take a second trip are the ones with slack (224-255)
# baseline (speedup 1.0000x reference)
.LBB0_145:
	v_writelane_b32 v252, s56, 34
	s_nop 1
	v_writelane_b32 v252, s57, 35
	s_or_b64 exec, exec, s[0:1]
	s_add_u32 s80, s10, 0xec00000
	s_addc_u32 s81, s11, 0
	s_add_u32 s25, s10, 0x3800000
	s_addc_u32 s26, s11, 0
	s_add_u32 s0, s10, 0x5a00000
	s_addc_u32 s1, s11, 0
	s_add_u32 s4, s10, 0x400000
	v_writelane_b32 v252, s4, 36
	s_addc_u32 s4, s11, 0
	s_cmpk_lt_i32 s2, 0x400
	v_writelane_b32 v252, s4, 37
	s_cselect_b64 s[4:5], -1, 0
	v_writelane_b32 v252, s4, 38
	s_ashr_i32 s33, s2, 31
	s_ashr_i32 s13, s96, 31
	v_writelane_b32 v252, s5, 39
	s_lshr_b32 s4, s33, 29
	s_add_i32 s5, s2, s4
	s_ashr_i32 s4, s5, 3
	s_and_b32 s5, s5, -8
	s_sub_i32 s6, s2, s5
	s_lshl_b32 s7, s6, 7
	s_and_b32 s5, s1, 0xffff
	s_add_u32 s14, s10, 0xf000200
	s_addc_u32 s15, s11, 0
	s_add_u32 s62, s10, 0xf000400
	s_addc_u32 s63, s11, 0
	s_add_u32 s28, s10, 0xf000500
	v_writelane_b32 v252, s14, 40
	s_addc_u32 s29, s11, 0
	v_lshl_add_u64 v[0:1], v[0:1], 2, s[52:53]
	v_writelane_b32 v252, s15, 41
	s_add_u32 s14, s10, 0xf000600
	s_addc_u32 s15, s11, 0
	v_writelane_b32 v252, s14, 42
	s_mov_b32 s69, 0
	s_mul_i32 s97, s97, s96
	v_writelane_b32 v252, s15, 43
	s_add_u32 s14, s10, 0xf000700
	s_addc_u32 s15, s11, 0
	v_writelane_b32 v252, s14, 44
	s_mul_i32 s97, s97, s54
	s_mov_b32 s83, 0x20000
	v_writelane_b32 v252, s15, 45
	s_add_u32 s14, s10, 0xf000800
	s_addc_u32 s15, s11, 0
	v_writelane_b32 v252, s14, 46
	s_mov_b32 s82, 0x7ffffff0
	v_mov_b32_e32 v161, 0
	v_writelane_b32 v252, s15, 47
	s_add_u32 s14, s10, 0xf000900
	s_addc_u32 s15, s11, 0
	v_writelane_b32 v252, s14, 48
	v_mov_b32_e32 v228, 1
	v_mov_b32_e32 v229, 0x358637bd
	v_writelane_b32 v252, s15, 49
	s_add_u32 s14, s10, 0xf000a00
	s_addc_u32 s15, s11, 0
	v_writelane_b32 v252, s14, 50
	v_mov_b32_e32 v230, 0xec00000
	v_mov_b32_e32 v231, 0xc0
	v_writelane_b32 v252, s15, 51
	s_add_u32 s14, s10, 0xf000b00
	s_addc_u32 s15, s11, 0
	v_writelane_b32 v252, s14, 52
	s_mov_b64 s[76:77], 0x80
	s_nop 0
	v_writelane_b32 v252, s15, 53
	s_add_u32 s14, s10, 0xf000c00
	s_addc_u32 s15, s11, 0
	v_writelane_b32 v252, s14, 54
	s_barrier
	s_nop 0
	v_writelane_b32 v252, s15, 55
	s_add_u32 s14, s10, 0xf000d00
	s_addc_u32 s15, s11, 0
	v_writelane_b32 v252, s14, 56
	s_nop 1
	v_writelane_b32 v252, s15, 57
	s_add_u32 s14, s10, 0xf000e00
	s_addc_u32 s15, s11, 0
	v_writelane_b32 v252, s14, 58
	s_nop 1
	v_writelane_b32 v252, s15, 59
	s_add_u32 s14, s10, 0xf000f00
	s_addc_u32 s15, s11, 0
	v_writelane_b32 v252, s14, 60
	s_nop 1
	v_writelane_b32 v252, s15, 61
	s_add_u32 s14, s10, 0xf001000
	s_addc_u32 s15, s11, 0
	s_add_u32 s86, s10, 0xf001100
	s_addc_u32 s87, s11, 0
	s_add_u32 s74, s10, 0xf001200
	s_addc_u32 s75, s11, 0
	s_add_u32 s78, s10, 0xf001300
	s_addc_u32 s79, s11, 0
	v_writelane_b32 v252, s14, 62
	s_cmp_eq_u32 s12, 15
	s_nop 0
	v_writelane_b32 v252, s15, 63
	s_cselect_b64 s[14:15], -1, 0
	v_writelane_b32 v253, s14, 0
	s_cmp_eq_u32 s12, 14
	s_nop 0
	v_writelane_b32 v253, s15, 1
	s_cselect_b64 s[14:15], -1, 0
	v_writelane_b32 v253, s14, 2
	s_cmp_eq_u32 s12, 13
	s_nop 0
	v_writelane_b32 v253, s15, 3
	s_cselect_b64 s[14:15], -1, 0
	v_writelane_b32 v253, s14, 4
	s_cmp_eq_u32 s12, 12
	s_nop 0
	v_writelane_b32 v253, s15, 5
	s_cselect_b64 s[14:15], -1, 0
	v_writelane_b32 v253, s14, 6
	s_cmp_eq_u32 s12, 11
	s_nop 0
	v_writelane_b32 v253, s15, 7
	s_cselect_b64 s[14:15], -1, 0
	v_writelane_b32 v253, s14, 8
	s_cmp_eq_u32 s12, 10
	s_nop 0
	v_writelane_b32 v253, s15, 9
	s_cselect_b64 s[14:15], -1, 0
	v_writelane_b32 v253, s14, 10
	s_cmp_eq_u32 s12, 9
	s_nop 0
	v_writelane_b32 v253, s15, 11
	s_cselect_b64 s[14:15], -1, 0
	v_writelane_b32 v253, s14, 12
	s_cmp_eq_u32 s12, 8
	s_nop 0
	v_writelane_b32 v253, s15, 13
	s_cselect_b64 s[14:15], -1, 0
	v_writelane_b32 v253, s14, 14
	s_cmp_eq_u32 s12, 7
	s_nop 0
	v_writelane_b32 v253, s15, 15
	s_mov_b64 s[14:15], 0x1400
	v_lshl_add_u64 v[218:219], v[0:1], 0, s[14:15]
	s_mov_b64 s[14:15], 0x2400
	v_lshl_add_u64 v[220:221], v[0:1], 0, s[14:15]
	s_cselect_b64 s[14:15], -1, 0
	v_writelane_b32 v253, s14, 16
	s_cmp_eq_u32 s12, 6
	s_nop 0
	v_writelane_b32 v253, s15, 17
	s_cselect_b64 s[14:15], -1, 0
	v_writelane_b32 v253, s14, 18
	s_cmp_eq_u32 s12, 5
	s_nop 0
	v_writelane_b32 v253, s15, 19
	s_cselect_b64 s[14:15], -1, 0
	v_writelane_b32 v253, s14, 20
	s_cmp_eq_u32 s12, 4
	s_nop 0
	v_writelane_b32 v253, s15, 21
	s_cselect_b64 s[14:15], -1, 0
	v_writelane_b32 v253, s14, 22
	s_cmp_eq_u32 s12, 3
	s_nop 0
	v_writelane_b32 v253, s15, 23
	s_cselect_b64 s[14:15], -1, 0
	v_writelane_b32 v253, s14, 24
	s_cmp_eq_u32 s12, 2
	s_nop 0
	v_writelane_b32 v253, s15, 25
	s_cselect_b64 s[14:15], -1, 0
	v_writelane_b32 v253, s14, 26
	s_cmp_eq_u32 s12, 1
	s_nop 0
	v_writelane_b32 v253, s15, 27
	s_cselect_b64 s[14:15], -1, 0
	v_writelane_b32 v253, s14, 28
	s_cmp_eq_u32 s12, 0
	s_nop 0
	v_writelane_b32 v253, s15, 29
	s_cselect_b64 s[14:15], -1, 0
	v_writelane_b32 v253, s14, 30
	s_nop 1
	v_writelane_b32 v253, s15, 31
	s_add_u32 s14, s10, 0xf003400
	s_addc_u32 s15, s11, 0
	v_writelane_b32 v253, s14, 32
	s_nop 1
	v_writelane_b32 v253, s15, 33
	s_add_u32 s14, s10, 0xf003500
	s_addc_u32 s15, s11, 0
	v_writelane_b32 v253, s14, 34
	s_add_u32 s12, s10, 0xef00000
	s_nop 0
	v_writelane_b32 v253, s15, 35
	v_writelane_b32 v253, s12, 36
	s_addc_u32 s12, s11, 0
	s_cmp_gt_i32 s2, 63
	v_writelane_b32 v253, s12, 37
	s_cselect_b64 s[14:15], -1, 0
	v_writelane_b32 v253, s14, 38
	s_add_i32 s12, s2, 0xffffff80
	s_nop 0
	v_writelane_b32 v253, s15, 39
	v_writelane_b32 v253, s12, 40
	s_sub_i32 s14, s2, 64
	s_add_i32 s12, s2, 0x80
	s_cmp_lt_u32 s55, 64
	v_writelane_b32 v253, s12, 41
	s_cselect_b64 s[16:17], -1, 0
	v_writelane_b32 v253, s16, 42
	v_readlane_b32 s12, v252, 32
	s_lshl_b32 s15, s12, 4
	v_writelane_b32 v253, s17, 43
	s_lshl_b32 s34, s12, 5
	s_add_i32 s12, s3, 0x1000
	v_writelane_b32 v253, s15, 44
	s_add_u32 s16, s10, 0x3600000
	v_writelane_b32 v253, s12, 45
	s_addc_u32 s17, s11, 0
	v_writelane_b32 v253, s16, 46
	s_nop 1
	v_writelane_b32 v253, s17, 47
	s_add_u32 s16, s10, 0x3700000
	s_addc_u32 s17, s11, 0
	v_writelane_b32 v253, s16, 48
	s_nop 1
	v_writelane_b32 v253, s17, 49
	s_add_u32 s16, s10, 0x3400000
	s_addc_u32 s17, s11, 0
	v_writelane_b32 v253, s16, 50
	s_add_u32 s12, s10, 0x5800000
	s_nop 0
	v_writelane_b32 v253, s17, 51
	v_writelane_b32 v253, s12, 52
	s_addc_u32 s12, s11, 0
	s_add_u32 s88, s10, 0xda00000
	s_addc_u32 s20, s11, 0
	s_add_u32 s16, s10, 0xec10000
	v_writelane_b32 v253, s12, 53
	s_addc_u32 s17, s11, 0
	v_writelane_b32 v253, s16, 54
	s_and_b32 s89, s20, 0xffff
	s_cmpk_lt_u32 s2, 0x40
	v_writelane_b32 v253, s17, 55
	v_writelane_b32 v253, s14, 56
	s_cselect_b64 s[14:15], -1, 0
	s_add_i32 s12, s2, 0xffffffe0
	s_add_i32 s16, s2, 0xffffff20
	s_cmpk_lt_u32 s2, 0xe0
	s_cselect_b32 s12, s12, s16
	v_writelane_b32 v253, s14, 57
	s_nop 0
	v_writelane_b32 v253, s15, 58
	s_add_u32 s14, s8, 0x6460000
	v_writelane_b32 v253, s12, 59
	s_addc_u32 s15, s9, 0
	v_writelane_b32 v253, s14, 60
	s_nop 1
	v_writelane_b32 v253, s15, 61
	s_add_u32 s14, s8, 0x4660000
	s_addc_u32 s15, s9, 0
	v_writelane_b32 v253, s14, 62
	s_nop 1
	v_writelane_b32 v253, s15, 63
	s_add_u32 s14, s8, 0x45e0000
	s_addc_u32 s15, s9, 0
	v_writelane_b32 v254, s14, 0
	s_nop 1
	v_writelane_b32 v254, s15, 1
	s_add_u32 s14, s8, 0x4400000
	s_addc_u32 s15, s9, 0
	s_add_u32 s35, s10, 0x5a01000
	v_writelane_b32 v254, s14, 2
	s_addc_u32 s36, s11, 0
	s_add_u32 s12, s10, 0x2400000
	v_writelane_b32 v254, s15, 3
	v_writelane_b32 v254, s12, 4
	s_addc_u32 s12, s11, 0
	s_cmpk_lt_i32 s2, 0x100
	v_writelane_b32 v254, s12, 5
	s_cselect_b64 s[14:15], -1, 0
	s_lshl_b32 s12, s6, 5
	s_add_u32 s19, s10, 0xda01000
	s_addc_u32 s21, s11, 0
	s_add_u32 s22, s10, 0xe400000
	s_addc_u32 s23, s11, 0
	v_writelane_b32 v254, s14, 6
	s_cmp_lt_i32 s2, 16
	s_nop 0
	v_writelane_b32 v254, s15, 7
	s_cselect_b64 s[14:15], -1, 0
	v_writelane_b32 v254, s14, 8
	s_lshl_b32 s38, s96, 4
	s_lshl_b32 s18, s6, 1
	v_writelane_b32 v254, s15, 9
	s_and_b32 s98, s2, 6
	s_lshl_b32 s98, s98, 3
	s_bfe_u32 s99, s2, 0x10005
	s_lshl_b32 s99, s99, 3
	s_or_b32 s98, s98, s99
	s_bfe_u32 s99, s2, 0x20003
	s_lshl_b32 s99, s99, 1
	s_or_b32 s98, s98, s99
	s_and_b32 s99, s2, 1
	s_or_b32 s98, s98, s99
	s_cmpk_lt_u32 s2, 0x40
	s_cselect_b32 s98, s98, s2
	s_lshr_b32 s14, s33, 28
	s_add_i32 s16, s98, s14
	s_ashr_i32 s17, s16, 4
	s_lshl_b32 s14, s17, 9
	s_ashr_i32 s15, s14, 31
	v_writelane_b32 v254, s19, 10
	s_lshl_b64 s[14:15], s[14:15], 1
	s_add_i32 s40, s38, 0xfffffc00
	v_writelane_b32 v254, s21, 11
	s_add_u32 s37, s19, s14
	v_writelane_b32 v254, s14, 12
	s_addc_u32 s39, s21, s15
	s_add_i32 s68, s17, -2
	v_writelane_b32 v254, s15, 13
	s_and_b32 s14, s16, -16
	s_sub_i32 s24, s98, s14
	s_lshl_b64 s[14:15], s[68:69], 21
	s_add_u32 s16, s22, s14
	v_writelane_b32 v254, s22, 14
	s_addc_u32 s17, s23, s15
	s_add_i32 s14, s98, 15
	s_cmp_lt_u32 s14, 31
	s_cselect_b32 s14, 0, 0x800
	v_writelane_b32 v254, s23, 15
	s_add_u32 s19, s88, s14
	v_writelane_b32 v254, s20, 16
	s_addc_u32 s20, s20, 0
	s_bfe_i32 s14, s24, 0x80000
	s_bfe_u32 s14, s14, 0x3000c
	s_add_i32 s14, s24, s14
	s_bfe_i32 s15, s14, 0x80000
	s_and_b32 s14, s14, 0xfff8
	s_sext_i32_i16 s15, s15
	s_sub_i32 s14, s24, s14
	s_ashr_i32 s15, s15, 3
	s_bfe_i32 s21, s14, 0x80000
	s_lshl_b32 s22, s14, 1
	v_writelane_b32 v254, s24, 17
	s_ashr_i32 s23, s24, 31
	v_writelane_b32 v254, s23, 18
	s_cmp_lt_i32 s6, 0
	s_mul_i32 s23, s6, 0x81
	s_cselect_b32 s7, s23, s7
	s_mul_i32 s23, s6, 33
	s_mul_i32 s6, s6, 3
	s_cselect_b32 s12, s23, s12
	s_cselect_b32 s18, s6, s18
	s_add_i32 s6, s7, s4
	s_ashr_i32 s7, s6, 31
	s_lshr_b32 s7, s7, 25
	s_add_i32 s7, s6, s7
	s_and_b32 s23, s7, 0xff80
	s_sub_i32 s6, s6, s23
	s_bfe_i32 s23, s6, 0x80000
	s_bfe_u32 s23, s23, 0x3000c
	s_add_i32 s23, s6, s23
	s_and_b32 s24, s23, 0xf8
	s_sub_i32 s6, s6, s24
	s_ashr_i32 s7, s7, 7
	s_bfe_i32 s23, s23, 0x80000
	s_lshl_b32 s7, s7, 3
	s_sext_i32_i16 s23, s23
	s_sext_i32_i8 s6, s6
	s_add_i32 s42, s7, s6
	s_ashr_i32 s6, s23, 3
	v_writelane_b32 v254, s6, 19
	s_lshr_b32 s6, s23, 3
	s_bfe_i64 s[6:7], s[6:7], 0x100000
	s_lshl_b64 s[6:7], s[6:7], 19
	v_writelane_b32 v254, s6, 20
	s_ashr_i32 s43, s42, 31
	s_mul_i32 s14, s14, 3
	v_writelane_b32 v254, s7, 21
	s_mov_b32 s6, s42
	v_writelane_b32 v254, s6, 22
	s_nop 1
	v_writelane_b32 v254, s7, 23
	s_lshl_b64 s[6:7], s[42:43], 19
	v_writelane_b32 v254, s25, 24
	s_add_u32 s6, s25, s6
	v_writelane_b32 v254, s26, 25
	s_addc_u32 s7, s26, s7
	s_add_u32 s24, s6, 0x40000
	v_writelane_b32 v254, s6, 26
	s_addc_u32 s25, s7, 0
	s_mov_b64 s[26:27], s[28:29]
	v_writelane_b32 v254, s7, 27
	s_add_i32 s6, s12, s4
	s_ashr_i32 s7, s6, 31
	s_lshr_b32 s7, s7, 27
	s_add_i32 s7, s6, s7
	s_and_b32 s12, s7, 0xffe0
	s_sub_i32 s6, s6, s12
	s_bfe_i32 s12, s6, 0x80000
	s_bfe_u32 s12, s12, 0x3000c
	s_add_i32 s12, s6, s12
	s_and_b32 s23, s12, 0xf8
	s_sub_i32 s6, s6, s23
	s_ashr_i32 s7, s7, 5
	s_bfe_i32 s12, s12, 0x80000
	v_writelane_b32 v254, s24, 28
	s_lshl_b32 s7, s7, 3
	s_sext_i32_i16 s12, s12
	s_sext_i32_i8 s6, s6
	v_writelane_b32 v254, s25, 29
	s_add_i32 s24, s7, s6
	s_ashr_i32 s6, s12, 3
	v_writelane_b32 v254, s6, 30
	s_lshr_b32 s6, s12, 3
	s_bfe_i64 s[6:7], s[6:7], 0x100000
	s_lshl_b64 s[6:7], s[6:7], 20
	v_writelane_b32 v254, s6, 31
	s_ashr_i32 s25, s24, 31
	s_mov_b32 s28, s69
	v_writelane_b32 v254, s7, 32
	s_mov_b32 s6, s24
	v_writelane_b32 v254, s6, 33
	s_nop 1
	v_writelane_b32 v254, s7, 34
	s_lshl_b64 s[6:7], s[24:25], 21
	s_add_u32 s6, s35, s6
	v_writelane_b32 v254, s35, 35
	s_addc_u32 s7, s36, s7
	v_writelane_b32 v254, s36, 36
	s_add_u32 s24, s6, 0x100000
	v_writelane_b32 v254, s6, 37
	s_addc_u32 s25, s7, 0
	s_add_i32 s4, s18, s4
	v_writelane_b32 v254, s7, 38
	s_ashr_i32 s6, s4, 31
	s_lshr_b32 s6, s6, 27
	s_add_i32 s6, s4, s6
	s_and_b32 s7, s6, 0xffffffe0
	s_ashr_i32 s6, s6, 5
	s_sub_i32 s23, s4, s7
	s_sext_i32_i16 s4, s21
	s_lshl_b32 s21, s6, 3
	v_writelane_b32 v254, s24, 39
	s_sub_i32 s6, 4, s21
	v_cvt_f32_i32_e32 v0, s23
	v_writelane_b32 v254, s25, 40
	s_min_u32 s24, s6, 8
	s_cmp_lt_i32 s4, 0
	s_cselect_b32 s4, s14, s22
	s_add_i32 s4, s4, s15
	s_bfe_i32 s6, s4, 0x80000
	s_bfe_u32 s6, s6, 0x2000d
	s_add_i32 s6, s4, s6
	s_bfe_i32 s7, s6, 0x80000
	s_sext_i32_i16 s12, s7
	s_and_b32 s6, s6, 0xfffc
	s_ashr_i32 s14, s12, 2
	s_lshr_b32 s12, s12, 2
	s_sub_i32 s4, s4, s6
	v_writelane_b32 v254, s14, 41
	s_bfe_i64 s[14:15], s[12:13], 0x100000
	s_bfe_i64 s[6:7], s[4:5], 0x80000
	s_lshl_b64 s[14:15], s[14:15], 20
	s_lshl_b64 s[6:7], s[6:7], 21
	v_writelane_b32 v254, s14, 42
	s_add_u32 s6, s37, s6
	s_addc_u32 s7, s39, s7
	v_writelane_b32 v254, s15, 43
	v_writelane_b32 v254, s37, 44
	v_writelane_b32 v254, s39, 45
	s_add_u32 s14, s6, 0x100000
	v_cvt_f32_ubyte0_e32 v1, s24
	v_writelane_b32 v254, s6, 46
	s_addc_u32 s15, s7, 0
	v_rcp_iflag_f32_e32 v2, v1
	s_cmp_lt_i32 s98, 32
	v_writelane_b32 v254, s7, 47
	s_cselect_b32 s6, s20, s17
	s_movk_i32 s7, 0x1000
	v_writelane_b32 v254, s14, 48
	s_cselect_b32 s12, s7, 0x400
	s_cselect_b32 s18, 13, 11
	s_cselect_b32 s92, s19, s16
	s_and_b32 s93, s6, 0xffff
	s_ashr_i32 s6, s23, 30
	v_writelane_b32 v254, s15, 49
	s_or_b32 s14, s6, 1
	v_mul_f32_e32 v2, v0, v2
	s_lshl_b32 s6, s12, 5
	v_trunc_f32_e32 v2, v2
	v_writelane_b32 v254, s6, 50
	v_fma_f32 v0, -v2, v1, v0
	v_writelane_b32 v254, s34, 51
	s_add_i32 s6, s34, 0
	v_writelane_b32 v254, s6, 52
	v_cmp_ge_f32_e64 s[6:7], |v0|, v1
	v_cvt_i32_f32_e32 v0, v2
	s_and_b64 s[6:7], s[6:7], exec
	s_sext_i32_i8 s4, s4
	v_writelane_b32 v254, s4, 53
	s_cselect_b32 s4, s14, 0
	v_readfirstlane_b32 s6, v0
	s_add_i32 s6, s6, s4
	s_mul_i32 s4, s6, s24
	s_sub_i32 s7, s23, s4
	s_sext_i32_i8 s7, s7
	s_add_i32 s14, s21, s7
	s_sext_i32_i8 s7, s6
	v_writelane_b32 v254, s7, 54
	s_bfe_i64 s[6:7], s[6:7], 0x80000
	s_lshl_b64 s[6:7], s[6:7], 20
	v_writelane_b32 v254, s6, 55
	s_ashr_i32 s15, s14, 31
	s_mov_b32 s4, s0
	v_writelane_b32 v254, s7, 56
	s_mul_i32 s6, s12, 0xc0
	v_writelane_b32 v254, s6, 57
	s_mov_b32 s6, s14
	v_writelane_b32 v254, s6, 58
	s_mov_b32 s12, 0xbfb8aa3b
	s_nop 0
	v_writelane_b32 v254, s7, 59
	s_lshl_b64 s[6:7], s[14:15], 21
	v_writelane_b32 v254, s6, 60
	s_mov_b64 s[14:15], 0xffffffff
	s_nop 0
	v_writelane_b32 v254, s7, 61
	s_add_u32 s6, s10, 0x5840080
	v_writelane_b32 v254, s6, 62
	s_addc_u32 s6, s11, 0
	v_writelane_b32 v254, s6, 63
	s_add_u32 s6, s10, 0x400100
	v_writelane_b32 v255, s6, 0
	s_addc_u32 s6, s11, 0
	s_ashr_i32 s39, s38, 31
	v_writelane_b32 v255, s6, 1
	s_add_i32 s6, s3, 0xfffbf800
	s_lshl_b64 s[70:71], s[38:39], 2
	v_writelane_b32 v255, s6, 2
	s_add_u32 s6, s8, 0x1000
	v_writelane_b32 v255, s6, 3
	s_addc_u32 s6, s9, 0
	v_writelane_b32 v255, s6, 4
	s_lshl_b32 s6, s2, 4
	s_addk_i32 s6, 0x3c00
	v_writelane_b32 v255, s6, 5
	s_add_i32 s6, 0, 0x20004
	v_writelane_b32 v255, s6, 6
	s_lshl_b64 s[6:7], s[38:39], 12
	v_writelane_b32 v255, s6, 7
	s_ashr_i32 s41, s40, 31
	s_lshl_b64 s[84:85], s[38:39], 11
	v_writelane_b32 v255, s7, 8
	s_mov_b32 s6, s38
	v_writelane_b32 v255, s6, 9
	s_nop 1
	v_writelane_b32 v255, s7, 10
	s_lshl_b64 s[6:7], s[38:39], 13
	v_writelane_b32 v255, s6, 11
	s_nop 1
	v_writelane_b32 v255, s7, 12
	s_lshl_b64 s[6:7], s[40:41], 2
	v_writelane_b32 v255, s6, 13
	s_nop 1
	v_writelane_b32 v255, s7, 14
	s_lshl_b64 s[6:7], s[40:41], 12
	v_writelane_b32 v255, s6, 15
	s_nop 1
	v_writelane_b32 v255, s7, 16
	s_lshl_b64 s[6:7], s[40:41], 11
	v_writelane_b32 v255, s6, 17
	s_nop 1
	v_writelane_b32 v255, s7, 18
	s_mov_b32 s6, s40
	v_writelane_b32 v255, s6, 19
	s_nop 1
	v_writelane_b32 v255, s7, 20
	s_lshl_b64 s[6:7], s[40:41], 13
	v_writelane_b32 v255, s6, 21
	s_nop 1
	v_writelane_b32 v255, s7, 22
	v_writelane_b32 v255, s62, 23
	s_nop 1
	v_writelane_b32 v255, s63, 24
	v_writelane_b32 v255, s26, 25
	s_nop 1
	v_writelane_b32 v255, s27, 26
	v_writelane_b32 v255, s80, 27
	s_nop 1
	v_writelane_b32 v255, s81, 28
	s_branch .LBB0_149
